# NSA fast path: far tiles software-pipelined across both halves, near tiles with hoisted LUT reads and -1e30 table masking (no cmp/cndmask), one barrier per two tiles, top-k rank-loop skip, SB quarter
# speedup vs baseline: 1.0285x; 1.0109x over previous
; #define LAS __attribute__((address_space(3)))
; __device__ __forceinline__ void sb_unit(const Params& p, LAS unsigned char* lds, int b, int hp, int qb, int tid, int lane, int wave) {
;     ...
;     const int col = lane & 31, hi = lane >> 5, w4 = wave & 3, hsel = wave >> 2, h = 2 * hp + hsel;
;     const int t = 128 * qb + 32 * w4 + col;
;     const size_t tok = (size_t)b * S + t;
;     const int tmaxw = 128 * qb + 32 * w4 + 31;
; __device__ __forceinline__ void phase4(const Params& p, LAS unsigned char* lds, int tid, int lane, int wave) {
;     for (int vb = blockIdx.x; vb < 256; vb += gridDim.x) {
;     const int v = (vb & 7) * 32 + (vb >> 3);
;     __syncthreads();
;     { const float* rel = p.in[2]; LAS float* lut = (LAS float*)(lds + LUT_OFF);
;       for (int e = tid; e < 1024; e += 512) { const int head = e >> 7, dist = e & 127;
;           int bk = dist; if (dist >= 16) { bk = 16 + (int)(logf((float)dist / 16.0f) / 2.0794415416798357f * 16.0f); bk = bk < 31 ? bk : 31; }
;           lut[e] = rel[bk * 8 + head] * LOG2E; } }
;     __syncthreads();
;     { const LAS float* lut = (const LAS float*)(lds + LUT_OFF); LAS float* l2 = (LAS float*)(lds + LUT2_OFF);
;       for (int e = tid; e < 8 * 260; e += 512) { const int head = e / 260, d = e % 260 - 68; l2[e] = d < 0 ? 0.f : lut[head * 128 + (d < 127 ? d : 127)]; } }
;     if (wave == 0) { const float* qg = p.in[13]; const float* kg = p.in[14]; LAS float* pm = (LAS float*)(lds + MISC4_OFF + 2304); const LAS float* lut = (const LAS float*)(lds + LUT_OFF);
.LBB0_428:
	s_or_b64 exec, exec, s[0:1]
	v_mov_b32_e32 v168, v218
	s_waitcnt lgkmcnt(0)
	s_barrier
	s_cmpk_gt_i32 s68, 0xff
	v_readfirstlane_b32 s0, v168
	s_cbranch_scc1 .LBB0_633
	v_writelane_b32 v251, s66, 30
	s_movk_i32 s1, 0x400
	v_cmp_gt_i32_e64 s[4:5], s1, v168
	v_writelane_b32 v251, s67, 31
	s_movk_i32 s1, 0x820
	v_writelane_b32 v251, s4, 32
	s_ashr_i32 s2, s0, 6
	s_cmp_lt_u32 s0, 64
	v_writelane_b32 v251, s5, 33
	v_cmp_gt_i32_e64 s[4:5], s1, v168
	v_and_b32_e32 v1, 63, v168
	v_lshlrev_b32_e32 v2, 2, v1
	v_writelane_b32 v251, s4, 34
	s_movk_i32 s36, 0x1ff
	s_mov_b32 s16, 0x41000000
	v_writelane_b32 v251, s5, 35
	s_cselect_b64 s[4:5], -1, 0
	v_writelane_b32 v251, s4, 36
	s_add_i32 s3, 0, 0x10000
	v_lshl_add_u32 v167, v1, 9, s3
	v_writelane_b32 v251, s5, 37
	v_cmp_gt_u32_e64 s[4:5], 8, v1
	s_ashr_i32 s0, s0, 8
	s_mov_b64 s[8:9], s[72:73]
	v_writelane_b32 v251, s4, 38
	s_mov_b64 s[20:21], s[84:85]
	v_lshlrev_b32_e32 v191, 2, v168
	v_writelane_b32 v251, s5, 39
	v_writelane_b32 v251, s3, 40
	s_add_i32 s3, 0, 0x21900
	v_writelane_b32 v251, s3, 41
	v_cmp_eq_u32_e64 s[4:5], 0, v1
	v_add_u32_e32 v171, s3, v2
	s_lshl_b32 s3, s2, 13
	v_writelane_b32 v251, s4, 42
	s_add_i32 s17, s3, 0
	s_lshl_b32 s3, s2, 10
	v_writelane_b32 v251, s5, 43
	s_lshl_b32 s4, s2, 3
	v_writelane_b32 v251, s3, 44
	s_add_i32 s92, s3, 0
	s_sub_i32 s3, s4, 31
	v_writelane_b32 v251, s3, 45
	s_lshl_b32 s3, s2, 8
	s_add_i32 s93, s3, 0
	s_add_i32 s3, s4, 0
	v_writelane_b32 v251, s4, 46
	s_add_i32 s3, s3, 0x21000
	v_writelane_b32 v251, s3, 47
	s_lshl_b32 s3, s2, 5
	s_and_b32 s3, s3, 0x60
	s_lshr_b32 s1, s2, 2
	s_mul_i32 s1, s1, 0x60
	s_xor_b32 s3, s3, s1
	v_and_b32_e32 v1, 0x7f, v168
	v_writelane_b32 v251, s3, 48
	s_lshl_b32 s3, s0, 6
	s_lshl_b32 s0, s0, 14
	v_cvt_f32_ubyte0_e32 v3, v1
	s_add_i32 s31, s0, 0
	v_mul_f32_e32 v3, 0x3d800000, v3
	s_mov_b32 s0, 0x800000
	v_cmp_gt_f32_e32 vcc, s0, v3
	s_mov_b32 s0, 0x3f317217
	s_lshl_b32 s2, s2, 2
	v_cndmask_b32_e64 v4, 0, 32, vcc
	v_ldexp_f32 v3, v3, v4
	v_log_f32_e32 v3, v3
	s_add_i32 s2, s2, 0
	v_writelane_b32 v251, s3, 49
	s_add_i32 s30, s2, 0x21080
	v_mul_f32_e32 v4, 0x3f317217, v3
	v_fma_f32 v4, v3, s0, -v4
	v_fmamk_f32 v4, v3, 0x3377d1cf, v4
	s_mov_b32 s0, 0x7f800000
	v_fmac_f32_e32 v4, 0x3f317217, v3
	v_cmp_lt_f32_e64 s[12:13], |v3|, s0
	s_mov_b32 s0, 0x40051592
	v_cmp_lt_u32_e64 s[10:11], 15, v1
	v_cndmask_b32_e64 v3, v3, v4, s[12:13]
	v_mov_b32_e32 v4, 0x41b17218
	v_cndmask_b32_e32 v4, 0, v4, vcc
	v_sub_f32_e32 v3, v3, v4
	v_div_scale_f32 v4, s[2:3], s0, s0, v3
	v_rcp_f32_e32 v5, v4
	v_readlane_b32 s4, v251, 1
	s_add_i32 s17, s17, 0x11000
	s_add_i32 s33, s93, 0x21100
	v_fma_f32 v6, -v4, v5, 1.0
	v_fmac_f32_e32 v5, v6, v5
	v_div_scale_f32 v6, vcc, v3, s0, v3
	v_mul_f32_e32 v7, v6, v5
	v_fma_f32 v8, -v4, v7, v6
	v_fmac_f32_e32 v7, v8, v5
	v_fma_f32 v4, -v4, v7, v6
	v_div_fmas_f32 v4, v4, v5, v7
	v_div_fixup_f32 v3, v4, s0, v3
	v_mul_f32_e32 v3, 0x41800000, v3
	v_cvt_i32_f32_e32 v3, v3
	v_readlane_b32 s6, v251, 3
	v_readlane_b32 s7, v251, 4
	s_add_u32 s2, s6, 0x10200000
	v_min_i32_e32 v3, 15, v3
	v_add_u32_e32 v3, 16, v3
	v_cndmask_b32_e64 v1, v1, v3, s[10:11]
	v_lshlrev_b32_e32 v170, 3, v1
	v_max_i32_e32 v1, 0x200, v168
	v_sub_u32_e32 v1, v1, v168
	s_addc_u32 s3, s7, 0
	v_mov_b32_e32 v3, 0
	v_add_u32_e32 v1, 0x1ff, v1
	v_readlane_b32 s5, v251, 2
	v_writelane_b32 v251, s2, 50
	v_lshl_add_u64 v[172:173], s[22:23], 0, v[2:3]
	v_lshl_add_u64 v[174:175], s[24:25], 0, v[2:3]
	v_lshrrev_b32_e32 v2, 9, v1
	v_writelane_b32 v251, s3, 51
	v_add_u32_e32 v4, 1, v2
	v_add_u32_e32 v2, -1, v2
	v_cmp_lt_u32_e64 s[2:3], s36, v1
	v_lshrrev_b32_e32 v5, 1, v2
	v_add_u32_e32 v5, 1, v5
	v_writelane_b32 v251, s2, 52
	v_and_b32_e32 v189, 3, v5
	v_and_b32_e32 v6, 0xfffffe, v4
	v_writelane_b32 v251, s3, 53
	v_cmp_lt_u32_e64 s[2:3], 5, v2
	s_add_u32 s0, s6, 0x18298e00
	s_mov_b64 s[12:13], s[76:77]
	v_writelane_b32 v251, s2, 54
	v_add_u32_e32 v2, 0, v191
	s_mov_b32 s1, 0
	v_writelane_b32 v251, s3, 55
	v_cmp_ne_u32_e64 s[2:3], 0, v189
	v_lshl_add_u32 v177, v6, 9, v168
	v_mov_b32_e32 v1, v170
	v_writelane_b32 v251, s2, 56
	v_add_u32_e32 v169, 0x200, v168
	v_and_b32_e32 v190, -4, v5
	v_writelane_b32 v251, s3, 57
	v_cmp_ne_u32_e64 s[2:3], v4, v6
	v_add_u32_e32 v192, 0x10000, v2
	v_add_u32_e32 v193, 0x10800, v2
	v_writelane_b32 v251, s2, 58
	s_mov_b32 s40, 0x3fb8aa3b
	s_mov_b32 s94, 0xf149f2ca
	v_writelane_b32 v251, s3, 59
	v_writelane_b32 v251, s0, 60
	s_addc_u32 s0, s7, 0
	v_writelane_b32 v251, s0, 61
	s_lshl_b32 s0, s68, 2
	v_writelane_b32 v251, s0, 62
	v_writelane_b32 v251, s70, 63
	s_lshl_b32 s0, s70, 2
	v_mbcnt_hi_u32_b32 v194, -1, v188
	v_writelane_b32 v250, s71, 0
	v_writelane_b32 v250, s0, 1
	s_add_u32 s0, s6, 0x18038e00
	v_writelane_b32 v250, s0, 2
	s_addc_u32 s0, s7, 0
	v_writelane_b32 v250, s0, 3
	s_add_u32 s0, s6, 0x18039200
	v_writelane_b32 v250, s0, 4
	s_addc_u32 s0, s7, 0
	v_writelane_b32 v250, s0, 5
	s_add_i32 s0, 0, 0x21a00
	v_writelane_b32 v250, s0, 6
	s_add_i32 s0, 0, 0x21908
	v_writelane_b32 v250, s0, 7
	s_add_i32 s0, 0, 0x21010
	v_writelane_b32 v250, s0, 8
	s_add_i32 s0, 0, 0x21020
	v_writelane_b32 v250, s0, 9
	s_add_i32 s0, 0, 0x21030
	v_writelane_b32 v250, s0, 10
	v_writelane_b32 v250, s68, 11
	v_writelane_b32 v250, s68, 12
	v_writelane_b32 v250, s8, 13
	s_mov_b64 s[6:7], 0x80
	s_mov_b64 s[38:39], 0x2000
	v_writelane_b32 v250, s9, 14
	v_writelane_b32 v250, s10, 15
	v_writelane_b32 v250, s11, 16
	v_writelane_b32 v250, s12, 17
	v_writelane_b32 v250, s13, 18
	v_writelane_b32 v250, s14, 19
	v_writelane_b32 v250, s15, 20
	v_writelane_b32 v250, s16, 21
	v_writelane_b32 v250, s17, 22
	v_writelane_b32 v250, s18, 23
	v_writelane_b32 v250, s19, 24
	v_writelane_b32 v250, s20, 25
	v_writelane_b32 v250, s21, 26
	v_writelane_b32 v250, s22, 27
	v_writelane_b32 v250, s23, 28
	s_mov_b32 s95, 0xefa18f08
	v_mov_b32_e32 v195, 0x260
	s_mov_b32 s88, 0x3f803f80
	v_mov_b32_e32 v196, 0x7f
	v_mov_b32_e32 v197, 0xf149f2ca
	v_mov_b32_e32 v198, 0x461c4000
	v_mov_b32_e32 v199, 0xce6e6b28
	v_mov_b32_e32 v200, 0x98000
	v_writelane_b32 v250, s30, 29
	v_writelane_b32 v250, s31, 30
	s_branch .LBB0_431

; #define LAS __attribute__((address_space(3)))
; __device__ __forceinline__ void phase4(const Params& p, LAS unsigned char* lds, int tid, int lane, int wave) {
;     ...
;     { const LAS float* lut = (const LAS float*)(lds + LUT_OFF); LAS float* l2 = (LAS float*)(lds + LUT2_OFF);
;       for (int e = tid; e < 8 * 260; e += 512) { const int head = e / 260, d = e % 260 - 68; l2[e] = d < 0 ? 0.f : lut[head * 128 + (d < 127 ? d : 127)]; } }
.LBB0_449:
	s_mov_b32 s0, 0x7e07e07f
	v_mul_hi_i32 v5, v4, s0
	v_lshrrev_b32_e32 v6, 31, v5
	v_ashrrev_i32_e32 v5, 7, v5
	v_add_u32_e32 v5, v5, v6
	v_mul_i32_i24_e32 v6, 0x104, v5
	v_sub_u32_e32 v7, v4, v6
	s_movk_i32 s0, 0x43
	v_cmp_lt_i32_e32 vcc, s0, v7
	v_mov_b32_e32 v6, 0xf149f2ca
	s_and_saveexec_b64 s[12:13], vcc
	s_cbranch_execz .LBB0_448
	v_min_u32_e32 v6, 0xc3, v7
	v_readlane_b32 s0, v251, 40
	v_lshlrev_b32_e32 v6, 2, v6
	s_nop 0
	v_lshl_add_u32 v5, v5, 9, s0
	s_movk_i32 s0, 0xfef0
	v_add3_u32 v5, v5, v6, s0
	ds_read_b32 v6, v5
	s_branch .LBB0_448

; #define LAS __attribute__((address_space(3)))
; #define RING_WAIT(ahead) do { if ((ahead) >= 2) WAITV_BAR(4); else if ((ahead) == 1) WAITV_BAR(2); else WAITV_BAR(0); } while (0)
; __device__ __forceinline__ int msb64(unsigned long long x) { return 63 - __builtin_clzll(x); }
;     __device__ __forceinline__ void issue(const bf16* k, size_t kpitch, const bf16* vt, size_t vpitch, int stage) const {
;         glds16(k + (size_t)r8 * kpitch + c8 * 8, (unsigned)__builtin_amdgcn_readfirstlane(base + (unsigned)stage * STG_BYTES));
;         glds16(vt + (size_t)r8 * vpitch + c8 * 8, (unsigned)__builtin_amdgcn_readfirstlane(base + (unsigned)stage * STG_BYTES + 8192u));
;     }
; __device__ __forceinline__ void nsa_unit(const Params& p, LAS unsigned char* lds, int b, int hkv, int i, int tid, int lane, int wave) {
;     ...
;         for (int it = 0; it < nt; ++it) {
;             const int j = msb64(crem); crem &= ~(1ull << j);
;             const int ahead = nt - 1 - it;
;             RING_WAIT(ahead);
;             if (it + 3 < nt) { const int ji = msb64(irem); irem &= ~(1ull << ji); rg.issue(Kb + (size_t)ji * 64 * ZW, ZW, Vb + (size_t)ji * 64 * ZW, ZW, (it + 3) & 3); }
;                 if ((wm >> j) & 1ull) {
;                     const LAS unsigned char* stg = lds + (it & 3) * STG_BYTES;
.LBB0_555:
	s_bitcmp1_b32 s79, 14
	s_cbranch_scc1 .Lpair_odd
	s_waitcnt vmcnt(0)
	s_barrier
	s_and_b32 s0, s79, 0xc000
	v_add_u32_e32 v254, s0, v203
	v_add_u32_e32 v125, v254, v204
	v_add_u32_e32 v126, v254, v205
	v_add_u32_e32 v127, v254, v206
	v_add_u32_e32 v128, v254, v207
	ds_read_b128 v[4:7], v125
	ds_read_b128 v[8:11], v126
	ds_read_b128 v[12:15], v127
	ds_read_b128 v[116:119], v128
	s_cmp_eq_u32 s79, 0
	s_cbranch_scc1 .Lpair_r2
	s_add_i32 s4, s9, -1
	s_cmp_ge_u32 s4, s68
	s_cbranch_scc1 .Lpair_r2
	s_flbit_i32_b64 s0, s[44:45]
	s_xor_b32 s0, s0, 63
	s_lshl_b64 s[2:3], 1, s0
	s_andn2_b64 s[44:45], s[44:45], s[2:3]
	s_add_i32 s2, s79, 0x8000
	s_mul_i32 s0, s0, 0x98000
	s_and_b32 s2, s2, 0xc000
	v_lshl_add_u64 v[252:253], v[120:121], 0, s[0:1]
	s_add_i32 s2, s2, s92
	s_mov_b32 s3, m0
	s_mov_b32 m0, s2
	s_nop 0
	global_load_lds_dwordx4 v[252:253], off
	s_mov_b32 m0, s3
	v_lshl_add_u64 v[252:253], v[122:123], 0, s[0:1]
	s_add_i32 s0, s2, 0x2000
	s_mov_b32 s2, m0
	s_mov_b32 m0, s0
	s_nop 0
	global_load_lds_dwordx4 v[252:253], off
	s_mov_b32 m0, s2
.Lpair_r2:
	s_cmp_ge_u32 s9, s68
	s_cbranch_scc1 .LBB0_563
	s_flbit_i32_b64 s0, s[44:45]
	s_xor_b32 s0, s0, 63
	s_lshl_b64 s[2:3], 1, s0
	s_andn2_b64 s[44:45], s[44:45], s[2:3]
	s_add_i32 s2, s79, 0xc000
	s_mul_i32 s0, s0, 0x98000
	s_and_b32 s2, s2, 0xc000
	v_lshl_add_u64 v[252:253], v[120:121], 0, s[0:1]
	s_add_i32 s2, s2, s92
	s_mov_b32 s3, m0
	s_mov_b32 m0, s2
	s_nop 0
	global_load_lds_dwordx4 v[252:253], off
	s_mov_b32 m0, s3
	v_lshl_add_u64 v[252:253], v[122:123], 0, s[0:1]
	s_add_i32 s0, s2, 0x2000
	s_mov_b32 s2, m0
	s_mov_b32 m0, s0
	s_nop 0
	global_load_lds_dwordx4 v[252:253], off
	s_mov_b32 m0, s2
	s_branch .LBB0_563
.Lpair_odd:
	s_and_b32 s0, s79, 0xc000
	v_add_u32_e32 v254, s0, v203
	v_add_u32_e32 v125, v254, v204
	v_add_u32_e32 v126, v254, v205
	v_add_u32_e32 v127, v254, v206
	v_add_u32_e32 v128, v254, v207
	ds_read_b128 v[4:7], v125
	ds_read_b128 v[8:11], v126
	ds_read_b128 v[12:15], v127
	ds_read_b128 v[116:119], v128
; __device__ __forceinline__ void pv_half_tr(const LAS unsigned char* vb, const unsigned (&pw)[8], const TrAddr& ta, int hf, f32x16& o0, f32x16& o1, f32x16& os, bf16x8 ones) {
; __device__ __forceinline__ void nsa_unit(const Params& p, LAS unsigned char* lds, int b, int hkv, int i, int tid, int lane, int wave) {
;     ...
;         for (int it = 0; it < nt; ++it) {
;             const int j = msb64(crem); crem &= ~(1ull << j);
;             const int ahead = nt - 1 - it;
;             RING_WAIT(ahead);
;             if (it + 3 < nt) { const int ji = msb64(irem); irem &= ~(1ull << ji); rg.issue(Kb + (size_t)ji * 64 * ZW, ZW, Vb + (size_t)ji * 64 * ZW, ZW, (it + 3) & 3); }
;                 if ((wm >> j) & 1ull) {
;                     const LAS unsigned char* stg = lds + (it & 3) * STG_BYTES;
;                     const int dj = i - j;
;                     const bool lsel = (lm >> j) & 1ull;
;                     const int db = 64 * dj + tq - 4 * hi;
; #pragma unroll
;                     for (int hf = 0; hf < 2; ++hf) {
;                         f32x16 s; unsigned pw[8];
;                         if (dj <= 2) {
;                             qk_half(stg, qf, col, hi, hf, s, -mref);
;                             const LAS float* l2p = (const LAS float*)(lds + LUT2_OFF) + head * 260 + db + 5;
; #pragma unroll
;                             for (int r = 0; r < 16; ++r) { const float x = s[r] + l2p[63 - KKOF(hf, r)]; s[r] = (lsel && KKOF(hf, r) <= db) ? ex2(x) : 0.f; }
; #pragma unroll
;                             for (int r = 0; r < 8; ++r) pw[r] = pk2(s[2 * r], s[2 * r + 1]);
;                         } else if (dj == 8) {
;                             qk_half_c(stg, qf, col, hi, hf, s, cfar);
; #pragma unroll
;                             for (int r = 0; r < 16; ++r) { const int d_ = db - KKOF(hf, r); s[r] = (lsel && d_ < dmax) ? ex2(s[r]) : 0.f; }
; #pragma unroll
;                             for (int r = 0; r < 8; ++r) pw[r] = pk2(s[2 * r], s[2 * r + 1]);
;                         } else {
;                             qk_half_c(stg, qf, col, hi, hf, s, cfar);
; #pragma unroll
;                             for (int r = 0; r < 8; ++r) { const unsigned w_ = pk2(ex2(s[2 * r]), ex2(s[2 * r + 1])); pw[r] = lsel ? w_ : 0u; }
;                         }
;                         pv_half_tr(stg + 8192, pw, tra, hf, o0, o1, os, ones);
;                     }
.LBB0_563:
	s_flbit_i32_b64 s0, s[34:35]
	s_xor_b32 s4, s0, 63
	s_lshl_b64 s[2:3], 1, s4
	s_and_b64 s[10:11], s[2:3], s[48:49]
	s_cmp_eq_u64 s[10:11], 0
	s_cbranch_scc1 .Lskip_tile
	s_and_b32 s0, s79, 0xc000
	s_add_i32 s0, s0, 0
	v_and_b32_e32 v253, s3, v214
	v_and_b32_e32 v252, s2, v215
	v_cmp_eq_u64_e64 s[22:23], 0, v[252:253]
	s_sub_i32 s4, s67, s4
	s_cmp_gt_i32 s4, 2
	s_cselect_b64 s[12:13], -1, 0
	s_cmp_lg_u32 s4, 8
	v_lshl_add_u32 v2, s4, 6, v212
	s_cselect_b64 s[10:11], -1, 0
	s_mov_b64 s[14:15], -1
	s_and_b64 vcc, exec, s[12:13]
	s_cbranch_vccz .LBB0_570
	s_and_b64 vcc, exec, s[10:11]
	s_cbranch_vccz .LBB0_567
	v_add3_u32 v248, s0, v208, v209
	v_add3_u32 v249, s0, v208, v210
	ds_read_b64_tr_b16 v[236:237], v248 offset:8192
	ds_read_b64_tr_b16 v[238:239], v248 offset:9216
	ds_read_b64_tr_b16 v[240:241], v249 offset:8192
	ds_read_b64_tr_b16 v[242:243], v249 offset:9216
	ds_read_b64_tr_b16 v[244:245], v248 offset:10240
	ds_read_b64_tr_b16 v[246:247], v248 offset:11264
	s_waitcnt lgkmcnt(9)
	v_mfma_f32_32x32x16_bf16 v[100:115], v[4:7], v[148:151], v[68:83]
	ds_read_b128 v[4:7], v125 offset:4096
	s_waitcnt lgkmcnt(9)
	v_mfma_f32_32x32x16_bf16 v[100:115], v[8:11], v[152:155], v[100:115]
	ds_read_b128 v[8:11], v126 offset:4096
	s_waitcnt lgkmcnt(9)
	v_mfma_f32_32x32x16_bf16 v[100:115], v[12:15], v[156:159], v[100:115]
	ds_read_b128 v[12:15], v127 offset:4096
	s_waitcnt lgkmcnt(9)
	v_mfma_f32_32x32x16_bf16 v[100:115], v[116:119], v[160:163], v[100:115]
	ds_read_b128 v[116:119], v128 offset:4096
	v_mov_b32_e32 v252, s88
	v_mov_b32_e32 v253, s88
	v_mov_b32_e32 v254, s88
	v_mov_b32_e32 v255, s88
	s_waitcnt lgkmcnt(3)
	v_mfma_f32_32x32x16_bf16 v[220:235], v[4:7], v[148:151], v[68:83]
	s_waitcnt lgkmcnt(2)
	v_mfma_f32_32x32x16_bf16 v[220:235], v[8:11], v[152:155], v[220:235]
	s_nop 2
	v_exp_f32_e32 v100, v100
	v_exp_f32_e32 v101, v101
	v_exp_f32_e32 v102, v102
	v_exp_f32_e32 v103, v103
	s_waitcnt lgkmcnt(1)
	v_mfma_f32_32x32x16_bf16 v[220:235], v[12:15], v[156:159], v[220:235]
	v_exp_f32_e32 v104, v104
	v_exp_f32_e32 v105, v105
	v_exp_f32_e32 v106, v106
	v_exp_f32_e32 v107, v107
	s_waitcnt lgkmcnt(0)
	v_mfma_f32_32x32x16_bf16 v[220:235], v[116:119], v[160:163], v[220:235]
	ds_read_b64_tr_b16 v[4:5], v248 offset:12288
	ds_read_b64_tr_b16 v[6:7], v248 offset:13312
	ds_read_b64_tr_b16 v[8:9], v249 offset:12288
	ds_read_b64_tr_b16 v[10:11], v249 offset:13312
	ds_read_b64_tr_b16 v[12:13], v248 offset:14336
	ds_read_b64_tr_b16 v[14:15], v248 offset:15360
	ds_read_b64_tr_b16 v[116:117], v249 offset:14336
	ds_read_b64_tr_b16 v[118:119], v249 offset:15360
	v_exp_f32_e32 v108, v108
	v_exp_f32_e32 v109, v109
	v_exp_f32_e32 v110, v110
	v_exp_f32_e32 v111, v111
	v_exp_f32_e32 v112, v112
	v_exp_f32_e32 v113, v113
	v_exp_f32_e32 v114, v114
	v_exp_f32_e32 v115, v115
	v_cvt_pk_bf16_f32 v100, v100, v101
	v_cvt_pk_bf16_f32 v101, v102, v103
	v_cvt_pk_bf16_f32 v102, v104, v105
	v_cvt_pk_bf16_f32 v103, v106, v107
	v_cvt_pk_bf16_f32 v104, v108, v109
	v_cvt_pk_bf16_f32 v105, v110, v111
	v_cvt_pk_bf16_f32 v106, v112, v113
	v_cvt_pk_bf16_f32 v107, v114, v115
	ds_read_b64_tr_b16 v[108:109], v249 offset:10240
	ds_read_b64_tr_b16 v[110:111], v249 offset:11264
	v_cndmask_b32_e64 v100, v100, 0, s[22:23]
	v_cndmask_b32_e64 v101, v101, 0, s[22:23]
	v_cndmask_b32_e64 v102, v102, 0, s[22:23]
	v_cndmask_b32_e64 v103, v103, 0, s[22:23]
	v_cndmask_b32_e64 v104, v104, 0, s[22:23]
	v_cndmask_b32_e64 v105, v105, 0, s[22:23]
	v_cndmask_b32_e64 v106, v106, 0, s[22:23]
	v_cndmask_b32_e64 v107, v107, 0, s[22:23]
	v_mfma_f32_32x32x16_bf16 v[36:51], v[236:239], v[100:103], v[36:51]
	v_exp_f32_e32 v220, v220
	v_exp_f32_e32 v221, v221
	v_exp_f32_e32 v222, v222
	v_exp_f32_e32 v223, v223
	v_mfma_f32_32x32x16_bf16 v[20:35], v[240:243], v[100:103], v[20:35]
	v_exp_f32_e32 v224, v224
	v_exp_f32_e32 v225, v225
	v_exp_f32_e32 v226, v226
	v_exp_f32_e32 v227, v227
	v_mfma_f32_32x32x16_bf16 v[52:67], v[252:255], v[100:103], v[52:67]
	v_exp_f32_e32 v228, v228
	v_exp_f32_e32 v229, v229
	v_exp_f32_e32 v230, v230
	v_exp_f32_e32 v231, v231
	v_mfma_f32_32x32x16_bf16 v[36:51], v[244:247], v[104:107], v[36:51]
	v_exp_f32_e32 v232, v232
	v_exp_f32_e32 v233, v233
	v_exp_f32_e32 v234, v234
	v_exp_f32_e32 v235, v235
	s_waitcnt lgkmcnt(0)
	v_mfma_f32_32x32x16_bf16 v[20:35], v[108:111], v[104:107], v[20:35]
	v_cvt_pk_bf16_f32 v220, v220, v221
	v_cvt_pk_bf16_f32 v221, v222, v223
	v_cvt_pk_bf16_f32 v222, v224, v225
	v_cvt_pk_bf16_f32 v223, v226, v227
	v_mfma_f32_32x32x16_bf16 v[52:67], v[252:255], v[104:107], v[52:67]
	v_cvt_pk_bf16_f32 v224, v228, v229
	v_cvt_pk_bf16_f32 v225, v230, v231
	v_cvt_pk_bf16_f32 v226, v232, v233
	v_cvt_pk_bf16_f32 v227, v234, v235
	v_cndmask_b32_e64 v220, v220, 0, s[22:23]
	v_cndmask_b32_e64 v221, v221, 0, s[22:23]
	v_cndmask_b32_e64 v222, v222, 0, s[22:23]
	v_cndmask_b32_e64 v223, v223, 0, s[22:23]
	v_cndmask_b32_e64 v224, v224, 0, s[22:23]
	v_cndmask_b32_e64 v225, v225, 0, s[22:23]
	v_cndmask_b32_e64 v226, v226, 0, s[22:23]
	v_cndmask_b32_e64 v227, v227, 0, s[22:23]
	v_mfma_f32_32x32x16_bf16 v[36:51], v[4:7], v[220:223], v[36:51]
	v_mfma_f32_32x32x16_bf16 v[20:35], v[8:11], v[220:223], v[20:35]
	v_mfma_f32_32x32x16_bf16 v[52:67], v[252:255], v[220:223], v[52:67]
	v_mfma_f32_32x32x16_bf16 v[36:51], v[12:15], v[224:227], v[36:51]
	v_mfma_f32_32x32x16_bf16 v[20:35], v[116:119], v[224:227], v[20:35]
	v_mfma_f32_32x32x16_bf16 v[52:67], v[252:255], v[224:227], v[52:67]
	s_branch .LBB0_554

; #define LAS __attribute__((address_space(3)))
; __device__ __forceinline__ unsigned pk2(float lo, float hi) { f32x2_t v = {lo, hi}; bf16x2_t b = __builtin_convertvector(v, bf16x2_t); return __builtin_bit_cast(unsigned, b); }
; __device__ __forceinline__ float ex2(float x) { return __builtin_amdgcn_exp2f(x); }
; #define MFMA32(a, b, c) __builtin_amdgcn_mfma_f32_32x32x16_bf16((a), (b), (c), 0, 0, 0)
; __device__ __forceinline__ void qk_half_c(const LAS unsigned char* kb, const bf16x8 (&qf)[4], int col, int hi, int hf, f32x16& s, const f32x16& c) {
;     const LAS unsigned char* k0 = kb + (32 * hf + col) * 128; const int k7 = col & 7;
;     bf16x8 a[4];
; #pragma unroll
;     for (int d0 = 0; d0 < 4; ++d0) a[d0] = *(const LAS bf16x8*)(k0 + (((2 * d0 + hi) ^ k7) << 4));
;     asm volatile("" ::: "memory");
;     s = MFMA32(a[0], qf[0], c);
; #pragma unroll
;     for (int d0 = 1; d0 < 4; ++d0) s = MFMA32(a[d0], qf[d0], s);
; }
; __device__ __forceinline__ void nsa_unit(const Params& p, LAS unsigned char* lds, int b, int hkv, int i, int tid, int lane, int wave) {
;     ...
;                         if (dj <= 2) {
;                             qk_half(stg, qf, col, hi, hf, s, -mref);
;                             const LAS float* l2p = (const LAS float*)(lds + LUT2_OFF) + head * 260 + db + 5;
; #pragma unroll
;                             for (int r = 0; r < 16; ++r) { const float x = s[r] + l2p[63 - KKOF(hf, r)]; s[r] = (lsel && KKOF(hf, r) <= db) ? ex2(x) : 0.f; }
; #pragma unroll
;                             for (int r = 0; r < 8; ++r) pw[r] = pk2(s[2 * r], s[2 * r + 1]);
.LBB0_570:
	s_andn2_b64 vcc, exec, s[14:15]
	v_lshl_add_u32 v16, v2, 2, v213
	s_cbranch_vccnz .LBB0_572
	v_cndmask_b32_e64 v236, v2, -1, s[22:23]
	v_lshl_add_u32 v16, v236, 2, v213
	ds_read2_b32 v[220:221], v16 offset0:67 offset1:68
	ds_read2_b32 v[222:223], v16 offset0:65 offset1:66
	ds_read2_b32 v[224:225], v16 offset0:59 offset1:60
	ds_read2_b32 v[226:227], v16 offset0:57 offset1:58
	ds_read2_b32 v[228:229], v16 offset0:51 offset1:52
	ds_read2_b32 v[230:231], v16 offset0:49 offset1:50
	ds_read2_b32 v[232:233], v16 offset0:43 offset1:44
	ds_read2_b32 v[234:235], v16 offset0:41 offset1:42
	s_waitcnt lgkmcnt(11)
	v_mfma_f32_32x32x16_bf16 v[100:115], v[4:7], v[148:151], v[84:99]
	s_waitcnt lgkmcnt(10)
	v_mfma_f32_32x32x16_bf16 v[100:115], v[8:11], v[152:155], v[100:115]
	s_waitcnt lgkmcnt(9)
	v_mfma_f32_32x32x16_bf16 v[100:115], v[12:15], v[156:159], v[100:115]
	s_waitcnt lgkmcnt(8)
	v_mfma_f32_32x32x16_bf16 v[100:115], v[116:119], v[160:163], v[100:115]
	s_waitcnt lgkmcnt(0)
	s_nop 10
	v_add_f32_e32 v100, v100, v221
	v_add_f32_e32 v101, v101, v220
	v_add_f32_e32 v102, v102, v223
	v_add_f32_e32 v103, v103, v222
	v_add_f32_e32 v104, v104, v225
	v_add_f32_e32 v105, v105, v224
	v_add_f32_e32 v106, v106, v227
	v_add_f32_e32 v107, v107, v226
	v_add_f32_e32 v108, v108, v229
	v_add_f32_e32 v109, v109, v228
	v_add_f32_e32 v110, v110, v231
	v_add_f32_e32 v111, v111, v230
	v_add_f32_e32 v112, v112, v233
	v_add_f32_e32 v113, v113, v232
	v_add_f32_e32 v114, v114, v235
	v_add_f32_e32 v115, v115, v234
	v_exp_f32_e32 v100, v100
	v_exp_f32_e32 v101, v101
	v_exp_f32_e32 v102, v102
	v_exp_f32_e32 v103, v103
	v_exp_f32_e32 v104, v104
	v_exp_f32_e32 v105, v105
	v_exp_f32_e32 v106, v106
	v_exp_f32_e32 v107, v107
	v_exp_f32_e32 v108, v108
	v_exp_f32_e32 v109, v109
	v_exp_f32_e32 v110, v110
	v_exp_f32_e32 v111, v111
	v_exp_f32_e32 v112, v112
	v_exp_f32_e32 v113, v113
	v_exp_f32_e32 v114, v114
	v_exp_f32_e32 v115, v115
	s_nop 0
	v_cvt_pk_bf16_f32 v100, v100, v101
	v_cvt_pk_bf16_f32 v101, v102, v103
	v_cvt_pk_bf16_f32 v102, v104, v105
	v_cvt_pk_bf16_f32 v103, v106, v107
	v_cvt_pk_bf16_f32 v104, v108, v109
	v_cvt_pk_bf16_f32 v105, v110, v111
	v_cvt_pk_bf16_f32 v106, v112, v113
	v_cvt_pk_bf16_f32 v107, v114, v115

; #define LAS __attribute__((address_space(3)))
; __device__ __forceinline__ unsigned pk2(float lo, float hi) { f32x2_t v = {lo, hi}; bf16x2_t b = __builtin_convertvector(v, bf16x2_t); return __builtin_bit_cast(unsigned, b); }
; __device__ __forceinline__ float ex2(float x) { return __builtin_amdgcn_exp2f(x); }
; #define RING_WAIT(ahead) do { if ((ahead) >= 2) WAITV_BAR(4); else if ((ahead) == 1) WAITV_BAR(2); else WAITV_BAR(0); } while (0)
; __device__ __forceinline__ int msb64(unsigned long long x) { return 63 - __builtin_clzll(x); }
; __device__ __forceinline__ void nsa_unit(const Params& p, LAS unsigned char* lds, int b, int hkv, int i, int tid, int lane, int wave) {
;     ...
;         for (int it = 0; it < nt; ++it) {
;             const int j = msb64(crem); crem &= ~(1ull << j);
;             const int ahead = nt - 1 - it;
;             RING_WAIT(ahead);
;             if (it + 3 < nt) { const int ji = msb64(irem); irem &= ~(1ull << ji); rg.issue(Kb + (size_t)ji * 64 * ZW, ZW, Vb + (size_t)ji * 64 * ZW, ZW, (it + 3) & 3); }
;                 if ((wm >> j) & 1ull) {
;     ...
;                         if (dj <= 2) {
;                             qk_half(stg, qf, col, hi, hf, s, -mref);
;                             const LAS float* l2p = (const LAS float*)(lds + LUT2_OFF) + head * 260 + db + 5;
; #pragma unroll
;                             for (int r = 0; r < 16; ++r) { const float x = s[r] + l2p[63 - KKOF(hf, r)]; s[r] = (lsel && KKOF(hf, r) <= db) ? ex2(x) : 0.f; }
; #pragma unroll
;                             for (int r = 0; r < 8; ++r) pw[r] = pk2(s[2 * r], s[2 * r + 1]);
.LBB0_578:
	s_andn2_b64 vcc, exec, s[14:15]
	s_cbranch_vccnz .LBB0_553
	v_cndmask_b32_e64 v236, v2, -1, s[22:23]
	v_lshl_add_u32 v16, v236, 2, v213
	ds_read2_b32 v[220:221], v16 offset0:35 offset1:36
	ds_read2_b32 v[222:223], v16 offset0:33 offset1:34
	ds_read2_b32 v[224:225], v16 offset0:27 offset1:28
	ds_read2_b32 v[226:227], v16 offset0:25 offset1:26
	ds_read2_b32 v[228:229], v16 offset0:19 offset1:20
	ds_read2_b32 v[230:231], v16 offset0:17 offset1:18
	ds_read2_b32 v[232:233], v16 offset0:11 offset1:12
	ds_read2_b32 v[234:235], v16 offset0:9 offset1:10
	s_waitcnt lgkmcnt(11)
	v_mfma_f32_32x32x16_bf16 v[100:115], v[4:7], v[148:151], v[84:99]
	s_waitcnt lgkmcnt(10)
	v_mfma_f32_32x32x16_bf16 v[100:115], v[8:11], v[152:155], v[100:115]
	s_waitcnt lgkmcnt(9)
	v_mfma_f32_32x32x16_bf16 v[100:115], v[12:15], v[156:159], v[100:115]
	s_waitcnt lgkmcnt(8)
	v_mfma_f32_32x32x16_bf16 v[100:115], v[116:119], v[160:163], v[100:115]
	s_waitcnt lgkmcnt(0)
	s_nop 10
	v_add_f32_e32 v100, v100, v221
	v_add_f32_e32 v101, v101, v220
	v_add_f32_e32 v102, v102, v223
	v_add_f32_e32 v103, v103, v222
	v_add_f32_e32 v104, v104, v225
	v_add_f32_e32 v105, v105, v224
	v_add_f32_e32 v106, v106, v227
	v_add_f32_e32 v107, v107, v226
	v_add_f32_e32 v108, v108, v229
	v_add_f32_e32 v109, v109, v228
	v_add_f32_e32 v110, v110, v231
	v_add_f32_e32 v111, v111, v230
	v_add_f32_e32 v112, v112, v233
	v_add_f32_e32 v113, v113, v232
	v_add_f32_e32 v114, v114, v235
	v_add_f32_e32 v115, v115, v234
	v_exp_f32_e32 v100, v100
	v_exp_f32_e32 v101, v101
	v_exp_f32_e32 v102, v102
	v_exp_f32_e32 v103, v103
	v_exp_f32_e32 v104, v104
	v_exp_f32_e32 v105, v105
	v_exp_f32_e32 v106, v106
	v_exp_f32_e32 v107, v107
	v_exp_f32_e32 v108, v108
	v_exp_f32_e32 v109, v109
	v_exp_f32_e32 v110, v110
	v_exp_f32_e32 v111, v111
	v_exp_f32_e32 v112, v112
	v_exp_f32_e32 v113, v113
	v_exp_f32_e32 v114, v114
	v_exp_f32_e32 v115, v115
	s_nop 0
	v_cvt_pk_bf16_f32 v220, v100, v101
	v_cvt_pk_bf16_f32 v221, v102, v103
	v_cvt_pk_bf16_f32 v222, v104, v105
	v_cvt_pk_bf16_f32 v223, v106, v107
	v_cvt_pk_bf16_f32 v100, v108, v109
	v_cvt_pk_bf16_f32 v101, v110, v111
	v_cvt_pk_bf16_f32 v102, v112, v113
	v_cvt_pk_bf16_f32 v103, v114, v115
	v_mov_b32_e32 v104, v220
	v_mov_b32_e32 v105, v221
	v_mov_b32_e32 v106, v222
	v_mov_b32_e32 v107, v223
	s_branch .LBB0_553
.Lskip_tile:
	s_waitcnt lgkmcnt(0)
	s_branch .LBB0_554

; __device__ __forceinline__ unsigned cvt_pk_bf16(float lo, float hi) { unsigned r; asm volatile("v_cvt_pk_bf16_f32 %0, %1, %2" : "=v"(r) : "v"(lo), "v"(hi)); return r; }
; __device__ __forceinline__ float bflo(unsigned u) { return __uint_as_float(u << 16); }
; __device__ __forceinline__ float bfhi(unsigned u) { return __uint_as_float(u & 0xffff0000u); }
; __device__ __forceinline__ float bflo(unsigned u) { return __uint_as_float(u << 16); }
; __device__ __forceinline__ float bfhi(unsigned u) { return __uint_as_float(u & 0xffff0000u); }
;     __device__ __forceinline__ void operator()(const f32x4 (&acc)[2][2][4][2], const Unit& u, int wr, int wc, int fr, int fq) const {
;         const int row0 = u.pm * BM + wr * 64 + fr; const int colt = u.pn * BM + wc * 32 + 8 * fq;
; #pragma unroll
;         for (int ai = 0; ai < 2; ++ai)
; #pragma unroll
;             for (int m = 0; m < 4; ++m) { const size_t row = (size_t)(row0 + ai * HALF + m * 16);
; #pragma unroll
;                 for (int bj = 0; bj < 2; ++bj) { const int col = colt + bj * HALF; const u32x4 gt = *(const u32x4*)(Zg + row * ZW + ZMB + col);
;                     const f32x4 a0 = acc[ai][bj][m][0], a1 = acc[ai][bj][m][1];
;                     u32x4 w; w.x = cvt_pk_bf16(a0[0] * gclamp(bflo(gt.x)), a0[1] * gclamp(bfhi(gt.x))); w.y = cvt_pk_bf16(a0[2] * gclamp(bflo(gt.y)), a0[3] * gclamp(bfhi(gt.y)));
;                     w.z = cvt_pk_bf16(a1[0] * gclamp(bflo(gt.z)), a1[1] * gclamp(bfhi(gt.z))); w.w = cvt_pk_bf16(a1[2] * gclamp(bflo(gt.w)), a1[3] * gclamp(bfhi(gt.w)));
;                     *(u32x4*)(Y + row * DM + col) = w; }
;                 if (m & 1) asm volatile("" ::: "memory"); }
;     }
.LBB0_707:
	v_readlane_b32 s24, v251, 24
	v_readlane_b32 s25, v251, 25
	v_ashrrev_i32_e32 v179, 31, v178
	v_ashrrev_i32_e32 v177, 31, v176
	v_mov_b64_e32 v[134:135], s[24:25]
	v_mad_i64_i32 v[130:131], s[24:25], v176, s44, v[134:135]
	v_lshl_add_u64 v[140:141], v[130:131], 0, s[14:15]
	v_lshlrev_b64 v[130:131], 1, v[178:179]
	v_lshl_add_u64 v[132:133], v[140:141], 0, v[130:131]
	v_mov_b32_e32 v240, 0x26000
	v_mov_b32_e32 v241, 0
	v_mov_b32_e32 v242, 0xbe000
	v_mov_b32_e32 v243, 0
	v_mov_b64_e32 v[244:245], v[132:133]
	global_load_dwordx4 v[146:149], v[244:245], off
	global_load_dwordx4 v[150:153], v[244:245], off offset:256
	v_lshl_add_u64 v[244:245], v[244:245], 0, v[240:241]
	global_load_dwordx4 v[154:157], v[244:245], off
	global_load_dwordx4 v[180:183], v[244:245], off offset:256
	v_lshl_add_u64 v[244:245], v[244:245], 0, v[240:241]
	global_load_dwordx4 v[184:187], v[244:245], off
	global_load_dwordx4 v[192:195], v[244:245], off offset:256
	v_lshl_add_u64 v[244:245], v[244:245], 0, v[240:241]
	global_load_dwordx4 v[196:199], v[244:245], off
	global_load_dwordx4 v[200:203], v[244:245], off offset:256
	v_lshl_add_u64 v[244:245], v[244:245], 0, v[242:243]
	global_load_dwordx4 v[204:207], v[244:245], off
	global_load_dwordx4 v[208:211], v[244:245], off offset:256
	v_lshl_add_u64 v[244:245], v[244:245], 0, v[240:241]
	global_load_dwordx4 v[212:215], v[244:245], off
	global_load_dwordx4 v[220:223], v[244:245], off offset:256
	v_lshl_add_u64 v[244:245], v[244:245], 0, v[240:241]
	global_load_dwordx4 v[224:227], v[244:245], off
	global_load_dwordx4 v[228:231], v[244:245], off offset:256
	v_lshl_add_u64 v[244:245], v[244:245], 0, v[240:241]
	global_load_dwordx4 v[232:235], v[244:245], off
	global_load_dwordx4 v[236:239], v[244:245], off offset:256
	v_or_b32_e32 v132, 0x80, v178
	v_ashrrev_i32_e32 v133, 31, v132
	v_lshlrev_b64 v[132:133], 1, v[132:133]
	v_lshl_add_u64 v[140:141], v[140:141], 0, v[132:133]
	v_readlane_b32 s26, v251, 22
	v_readlane_b32 s27, v251, 23
	s_andn2_b64 vcc, exec, s[0:1]
	s_mov_b64 s[0:1], -1
	s_waitcnt vmcnt(15)
	v_lshlrev_b32_e32 v142, 16, v146
	v_and_b32_e32 v136, 0xffff0000, v146
	v_lshlrev_b32_e32 v143, 16, v147
	v_and_b32_e32 v137, 0xffff0000, v147
	v_lshlrev_b32_e32 v145, 16, v149
	v_and_b32_e32 v139, 0xffff0000, v149
	v_lshlrev_b32_e32 v144, 16, v148
	v_and_b32_e32 v138, 0xffff0000, v148
	v_max_f32_e32 v142, v142, v142
	v_max_f32_e32 v136, v136, v136
	v_max_f32_e32 v143, v143, v143
	v_max_f32_e32 v137, v137, v137
	v_max_f32_e32 v139, v139, v139
	v_max_f32_e32 v144, v144, v144
	v_max_f32_e32 v138, v138, v138
	v_max_f32_e32 v145, v145, v145
	v_max_f32_e32 v142, 0x1e3ce508, v142
	v_max_f32_e32 v136, 0x1e3ce508, v136
	v_max_f32_e32 v143, 0x1e3ce508, v143
	v_max_f32_e32 v137, 0x1e3ce508, v137
	v_max_f32_e32 v139, 0x1e3ce508, v139
	v_max_f32_e32 v144, 0x1e3ce508, v144
	v_max_f32_e32 v138, 0x1e3ce508, v138
	v_max_f32_e32 v145, 0x1e3ce508, v145
	v_mul_f32_e32 v126, v126, v142
	v_mul_f32_e32 v127, v127, v136
	v_mul_f32_e32 v128, v128, v143
	v_mul_f32_e32 v129, v129, v137
	v_mul_f32_e32 v125, v125, v139
	v_mul_f32_e32 v136, v122, v144
	v_mul_f32_e32 v137, v123, v138
	v_mul_f32_e32 v138, v124, v145
	v_cvt_pk_bf16_f32 v122, v126, v127
	v_cvt_pk_bf16_f32 v123, v128, v129
	v_cvt_pk_bf16_f32 v124, v136, v137
	v_cvt_pk_bf16_f32 v125, v138, v125
	s_nop 0
	v_lshlrev_b64 v[138:139], 11, v[176:177]
	v_lshl_add_u64 v[138:139], s[26:27], 0, v[138:139]
	v_lshl_add_u64 v[138:139], v[138:139], 0, v[130:131]
	v_or_b32_e32 v136, 16, v176
	global_store_dwordx4 v[138:139], v[122:125], off
	v_mad_i64_i32 v[140:141], s[24:25], v136, s44, v[134:135]
	v_lshl_add_u64 v[140:141], v[140:141], 0, s[14:15]
	v_lshl_add_u64 v[142:143], v[140:141], 0, v[130:131]
	v_ashrrev_i32_e32 v137, 31, v136
	s_waitcnt vmcnt(15)
	v_lshlrev_b32_e32 v122, 16, v150
	v_and_b32_e32 v123, 0xffff0000, v150
	v_lshlrev_b32_e32 v124, 16, v151
	v_and_b32_e32 v125, 0xffff0000, v151
	v_lshlrev_b32_e32 v126, 16, v152
	v_and_b32_e32 v127, 0xffff0000, v152
	v_lshlrev_b32_e32 v128, 16, v153
	v_and_b32_e32 v129, 0xffff0000, v153
	v_max_f32_e32 v122, v122, v122
	v_max_f32_e32 v123, v123, v123
	v_max_f32_e32 v124, v124, v124
	v_max_f32_e32 v125, v125, v125
	v_max_f32_e32 v129, v129, v129
	v_max_f32_e32 v126, v126, v126
	v_max_f32_e32 v127, v127, v127
	v_max_f32_e32 v128, v128, v128
	v_max_f32_e32 v122, 0x1e3ce508, v122
	v_max_f32_e32 v123, 0x1e3ce508, v123
	v_max_f32_e32 v124, 0x1e3ce508, v124
	v_max_f32_e32 v125, 0x1e3ce508, v125
	v_max_f32_e32 v129, 0x1e3ce508, v129
	v_max_f32_e32 v126, 0x1e3ce508, v126
	v_max_f32_e32 v127, 0x1e3ce508, v127
	v_max_f32_e32 v128, 0x1e3ce508, v128
	v_mul_f32_e32 v118, v118, v122
	v_mul_f32_e32 v119, v119, v123
	v_mul_f32_e32 v120, v120, v124
	v_mul_f32_e32 v121, v121, v125
	v_mul_f32_e32 v117, v117, v129
	v_mul_f32_e32 v122, v114, v126
	v_mul_f32_e32 v123, v115, v127
	v_mul_f32_e32 v124, v116, v128
	v_cvt_pk_bf16_f32 v114, v118, v119
	v_cvt_pk_bf16_f32 v115, v120, v121
	v_cvt_pk_bf16_f32 v116, v122, v123
	v_cvt_pk_bf16_f32 v117, v124, v117
	s_nop 0
	v_lshl_add_u64 v[122:123], v[140:141], 0, v[132:133]
	global_store_dwordx4 v[138:139], v[114:117], off offset:256
	s_waitcnt vmcnt(15)
; __device__ __forceinline__ unsigned cvt_pk_bf16(float lo, float hi) { unsigned r; asm volatile("v_cvt_pk_bf16_f32 %0, %1, %2" : "=v"(r) : "v"(lo), "v"(hi)); return r; }
; __device__ __forceinline__ float bflo(unsigned u) { return __uint_as_float(u << 16); }
; __device__ __forceinline__ float bfhi(unsigned u) { return __uint_as_float(u & 0xffff0000u); }
; __device__ __forceinline__ float bflo(unsigned u) { return __uint_as_float(u << 16); }
; __device__ __forceinline__ float bfhi(unsigned u) { return __uint_as_float(u & 0xffff0000u); }
;     __device__ __forceinline__ void operator()(const f32x4 (&acc)[2][2][4][2], const Unit& u, int wr, int wc, int fr, int fq) const {
;         const int row0 = u.pm * BM + wr * 64 + fr; const int colt = u.pn * BM + wc * 32 + 8 * fq;
; #pragma unroll
;         for (int ai = 0; ai < 2; ++ai)
; #pragma unroll
;             for (int m = 0; m < 4; ++m) { const size_t row = (size_t)(row0 + ai * HALF + m * 16);
; #pragma unroll
;                 for (int bj = 0; bj < 2; ++bj) { const int col = colt + bj * HALF; const u32x4 gt = *(const u32x4*)(Zg + row * ZW + ZMB + col);
;                     const f32x4 a0 = acc[ai][bj][m][0], a1 = acc[ai][bj][m][1];
;                     u32x4 w; w.x = cvt_pk_bf16(a0[0] * gclamp(bflo(gt.x)), a0[1] * gclamp(bfhi(gt.x))); w.y = cvt_pk_bf16(a0[2] * gclamp(bflo(gt.y)), a0[3] * gclamp(bfhi(gt.y)));
;                     w.z = cvt_pk_bf16(a1[0] * gclamp(bflo(gt.z)), a1[1] * gclamp(bfhi(gt.z))); w.w = cvt_pk_bf16(a1[2] * gclamp(bflo(gt.w)), a1[3] * gclamp(bfhi(gt.w)));
;                     *(u32x4*)(Y + row * DM + col) = w; }
;                 if (m & 1) asm volatile("" ::: "memory"); }
;     }
	s_nop 0
	v_lshlrev_b32_e32 v114, 16, v154
	v_and_b32_e32 v115, 0xffff0000, v154
	v_lshlrev_b32_e32 v116, 16, v155
	v_and_b32_e32 v117, 0xffff0000, v155
	v_lshlrev_b32_e32 v118, 16, v156
	v_and_b32_e32 v119, 0xffff0000, v156
	v_lshlrev_b32_e32 v120, 16, v157
	v_and_b32_e32 v121, 0xffff0000, v157
	v_max_f32_e32 v114, v114, v114
	v_max_f32_e32 v115, v115, v115
	v_max_f32_e32 v116, v116, v116
	v_max_f32_e32 v117, v117, v117
	v_max_f32_e32 v121, v121, v121
	v_max_f32_e32 v118, v118, v118
	v_max_f32_e32 v119, v119, v119
	v_max_f32_e32 v120, v120, v120
	v_max_f32_e32 v114, 0x1e3ce508, v114
	v_max_f32_e32 v115, 0x1e3ce508, v115
	v_max_f32_e32 v116, 0x1e3ce508, v116
	v_max_f32_e32 v117, 0x1e3ce508, v117
	v_max_f32_e32 v121, 0x1e3ce508, v121
	v_max_f32_e32 v118, 0x1e3ce508, v118
	v_max_f32_e32 v119, 0x1e3ce508, v119
	v_max_f32_e32 v120, 0x1e3ce508, v120
	v_mul_f32_e32 v110, v110, v114
	v_mul_f32_e32 v111, v111, v115
	v_mul_f32_e32 v112, v112, v116
	v_mul_f32_e32 v113, v113, v117
	v_mul_f32_e32 v109, v109, v121
	v_mul_f32_e32 v114, v106, v118
	v_mul_f32_e32 v115, v107, v119
	v_mul_f32_e32 v116, v108, v120
	v_cvt_pk_bf16_f32 v106, v110, v111
	v_cvt_pk_bf16_f32 v107, v112, v113
	v_cvt_pk_bf16_f32 v108, v114, v115
	v_cvt_pk_bf16_f32 v109, v116, v109
	s_nop 0
	v_lshlrev_b64 v[118:119], 11, v[136:137]
	v_lshl_add_u64 v[118:119], s[26:27], 0, v[118:119]
	v_lshl_add_u64 v[118:119], v[118:119], 0, v[130:131]
	global_store_dwordx4 v[118:119], v[106:109], off
	v_or_b32_e32 v114, 32, v176
	v_mad_i64_i32 v[116:117], s[24:25], v114, s44, v[134:135]
	v_lshl_add_u64 v[116:117], v[116:117], 0, s[14:15]
	v_lshl_add_u64 v[120:121], v[116:117], 0, v[130:131]
	v_ashrrev_i32_e32 v115, 31, v114
	s_waitcnt vmcnt(15)
	v_lshlrev_b32_e32 v106, 16, v180
	v_and_b32_e32 v107, 0xffff0000, v180
	v_lshlrev_b32_e32 v108, 16, v181
	v_and_b32_e32 v109, 0xffff0000, v181
	v_lshlrev_b32_e32 v110, 16, v182
	v_and_b32_e32 v111, 0xffff0000, v182
	v_lshlrev_b32_e32 v112, 16, v183
	v_and_b32_e32 v113, 0xffff0000, v183
	v_max_f32_e32 v113, v113, v113
	v_max_f32_e32 v106, v106, v106
	v_max_f32_e32 v107, v107, v107
	v_max_f32_e32 v108, v108, v108
	v_max_f32_e32 v109, v109, v109
	v_max_f32_e32 v110, v110, v110
	v_max_f32_e32 v111, v111, v111
	v_max_f32_e32 v112, v112, v112
	v_max_f32_e32 v113, 0x1e3ce508, v113
	v_max_f32_e32 v106, 0x1e3ce508, v106
	v_max_f32_e32 v107, 0x1e3ce508, v107
	v_max_f32_e32 v108, 0x1e3ce508, v108
	v_max_f32_e32 v109, 0x1e3ce508, v109
	v_max_f32_e32 v110, 0x1e3ce508, v110
	v_max_f32_e32 v111, 0x1e3ce508, v111
	v_max_f32_e32 v112, 0x1e3ce508, v112
	v_mul_f32_e32 v101, v101, v113
	v_mul_f32_e32 v102, v102, v106
	v_mul_f32_e32 v103, v103, v107
	v_mul_f32_e32 v104, v104, v108
	v_mul_f32_e32 v105, v105, v109
	v_mul_f32_e32 v106, v98, v110
	v_mul_f32_e32 v107, v99, v111
	v_mul_f32_e32 v108, v100, v112
	v_cvt_pk_bf16_f32 v98, v102, v103
	v_cvt_pk_bf16_f32 v99, v104, v105
	v_cvt_pk_bf16_f32 v100, v106, v107
	v_cvt_pk_bf16_f32 v101, v108, v101
	global_store_dwordx4 v[118:119], v[98:101], off offset:256
	s_nop 0
	v_lshl_add_u64 v[102:103], v[116:117], 0, v[132:133]
	s_waitcnt vmcnt(15)
	v_lshlrev_b32_e32 v104, 16, v184
	v_and_b32_e32 v98, 0xffff0000, v184
	v_lshlrev_b32_e32 v105, 16, v185
	v_and_b32_e32 v99, 0xffff0000, v185
	v_lshlrev_b32_e32 v107, 16, v187
	v_and_b32_e32 v101, 0xffff0000, v187
	v_lshlrev_b32_e32 v106, 16, v186
	v_and_b32_e32 v100, 0xffff0000, v186
	v_max_f32_e32 v104, v104, v104
	v_max_f32_e32 v98, v98, v98
	v_max_f32_e32 v105, v105, v105
	v_max_f32_e32 v99, v99, v99
	v_max_f32_e32 v101, v101, v101
	v_max_f32_e32 v106, v106, v106
	v_max_f32_e32 v100, v100, v100
	v_max_f32_e32 v107, v107, v107
	v_max_f32_e32 v104, 0x1e3ce508, v104
	v_max_f32_e32 v98, 0x1e3ce508, v98
	v_max_f32_e32 v105, 0x1e3ce508, v105
	v_max_f32_e32 v99, 0x1e3ce508, v99
	v_max_f32_e32 v101, 0x1e3ce508, v101
	v_max_f32_e32 v106, 0x1e3ce508, v106
	v_max_f32_e32 v100, 0x1e3ce508, v100
	v_max_f32_e32 v107, 0x1e3ce508, v107
	v_mul_f32_e32 v94, v94, v104
	v_mul_f32_e32 v95, v95, v98
	v_mul_f32_e32 v96, v96, v105
	v_mul_f32_e32 v97, v97, v99
	v_mul_f32_e32 v93, v93, v101
	v_mul_f32_e32 v98, v90, v106
	v_mul_f32_e32 v99, v91, v100
	v_mul_f32_e32 v100, v92, v107
	v_cvt_pk_bf16_f32 v90, v94, v95
	v_cvt_pk_bf16_f32 v91, v96, v97
	v_cvt_pk_bf16_f32 v92, v98, v99
	v_cvt_pk_bf16_f32 v93, v100, v93
	s_nop 0
	v_lshlrev_b64 v[102:103], 11, v[114:115]
	v_lshl_add_u64 v[102:103], s[26:27], 0, v[102:103]
	v_lshl_add_u64 v[102:103], v[102:103], 0, v[130:131]
	v_or_b32_e32 v98, 48, v176
	global_store_dwordx4 v[102:103], v[90:93], off
	v_mad_i64_i32 v[100:101], s[24:25], v98, s44, v[134:135]
	v_lshl_add_u64 v[100:101], v[100:101], 0, s[14:15]
	v_lshl_add_u64 v[104:105], v[100:101], 0, v[130:131]
	v_ashrrev_i32_e32 v99, 31, v98
	s_waitcnt vmcnt(15)
	v_lshlrev_b32_e32 v90, 16, v192
	v_and_b32_e32 v91, 0xffff0000, v192
	v_lshlrev_b32_e32 v92, 16, v193
	v_and_b32_e32 v93, 0xffff0000, v193
	v_lshlrev_b32_e32 v94, 16, v194
	v_and_b32_e32 v95, 0xffff0000, v194
	v_lshlrev_b32_e32 v96, 16, v195
	v_and_b32_e32 v97, 0xffff0000, v195
	v_max_f32_e32 v90, v90, v90
	v_max_f32_e32 v91, v91, v91
	v_max_f32_e32 v92, v92, v92
	v_max_f32_e32 v93, v93, v93
	v_max_f32_e32 v97, v97, v97
	v_max_f32_e32 v94, v94, v94
	v_max_f32_e32 v95, v95, v95
	v_max_f32_e32 v96, v96, v96
	v_max_f32_e32 v90, 0x1e3ce508, v90
	v_max_f32_e32 v91, 0x1e3ce508, v91
	v_max_f32_e32 v92, 0x1e3ce508, v92
	v_max_f32_e32 v93, 0x1e3ce508, v93
	v_max_f32_e32 v97, 0x1e3ce508, v97
	v_max_f32_e32 v94, 0x1e3ce508, v94
	v_max_f32_e32 v95, 0x1e3ce508, v95
	v_max_f32_e32 v96, 0x1e3ce508, v96
	v_mul_f32_e32 v86, v86, v90
	v_mul_f32_e32 v87, v87, v91
	v_mul_f32_e32 v88, v88, v92
	v_mul_f32_e32 v89, v89, v93
	v_mul_f32_e32 v85, v85, v97
	v_mul_f32_e32 v90, v82, v94
	v_mul_f32_e32 v91, v83, v95
	v_mul_f32_e32 v92, v84, v96
	v_cvt_pk_bf16_f32 v82, v86, v87
	v_cvt_pk_bf16_f32 v83, v88, v89
	v_cvt_pk_bf16_f32 v84, v90, v91
	v_cvt_pk_bf16_f32 v85, v92, v85
	s_nop 0
	v_lshl_add_u64 v[90:91], v[100:101], 0, v[132:133]
	global_store_dwordx4 v[102:103], v[82:85], off offset:256
	s_waitcnt vmcnt(15)
; __device__ __forceinline__ unsigned cvt_pk_bf16(float lo, float hi) { unsigned r; asm volatile("v_cvt_pk_bf16_f32 %0, %1, %2" : "=v"(r) : "v"(lo), "v"(hi)); return r; }
; __device__ __forceinline__ float bflo(unsigned u) { return __uint_as_float(u << 16); }
; __device__ __forceinline__ float bfhi(unsigned u) { return __uint_as_float(u & 0xffff0000u); }
; __device__ __forceinline__ float bflo(unsigned u) { return __uint_as_float(u << 16); }
; __device__ __forceinline__ float bfhi(unsigned u) { return __uint_as_float(u & 0xffff0000u); }
;     __device__ __forceinline__ void operator()(const f32x4 (&acc)[2][2][4][2], const Unit& u, int wr, int wc, int fr, int fq) const {
;         const int row0 = u.pm * BM + wr * 64 + fr; const int colt = u.pn * BM + wc * 32 + 8 * fq;
; #pragma unroll
;         for (int ai = 0; ai < 2; ++ai)
; #pragma unroll
;             for (int m = 0; m < 4; ++m) { const size_t row = (size_t)(row0 + ai * HALF + m * 16);
; #pragma unroll
;                 for (int bj = 0; bj < 2; ++bj) { const int col = colt + bj * HALF; const u32x4 gt = *(const u32x4*)(Zg + row * ZW + ZMB + col);
;                     const f32x4 a0 = acc[ai][bj][m][0], a1 = acc[ai][bj][m][1];
;                     u32x4 w; w.x = cvt_pk_bf16(a0[0] * gclamp(bflo(gt.x)), a0[1] * gclamp(bfhi(gt.x))); w.y = cvt_pk_bf16(a0[2] * gclamp(bflo(gt.y)), a0[3] * gclamp(bfhi(gt.y)));
;                     w.z = cvt_pk_bf16(a1[0] * gclamp(bflo(gt.z)), a1[1] * gclamp(bfhi(gt.z))); w.w = cvt_pk_bf16(a1[2] * gclamp(bflo(gt.w)), a1[3] * gclamp(bfhi(gt.w)));
;                     *(u32x4*)(Y + row * DM + col) = w; }
;                 if (m & 1) asm volatile("" ::: "memory"); }
;     }
	s_nop 0
	v_lshlrev_b32_e32 v82, 16, v196
	v_and_b32_e32 v83, 0xffff0000, v196
	v_lshlrev_b32_e32 v84, 16, v197
	v_and_b32_e32 v85, 0xffff0000, v197
	v_lshlrev_b32_e32 v86, 16, v198
	v_and_b32_e32 v87, 0xffff0000, v198
	v_lshlrev_b32_e32 v88, 16, v199
	v_and_b32_e32 v89, 0xffff0000, v199
	v_max_f32_e32 v82, v82, v82
	v_max_f32_e32 v83, v83, v83
	v_max_f32_e32 v84, v84, v84
	v_max_f32_e32 v85, v85, v85
	v_max_f32_e32 v89, v89, v89
	v_max_f32_e32 v86, v86, v86
	v_max_f32_e32 v87, v87, v87
	v_max_f32_e32 v88, v88, v88
	v_max_f32_e32 v82, 0x1e3ce508, v82
	v_max_f32_e32 v83, 0x1e3ce508, v83
	v_max_f32_e32 v84, 0x1e3ce508, v84
	v_max_f32_e32 v85, 0x1e3ce508, v85
	v_max_f32_e32 v89, 0x1e3ce508, v89
	v_max_f32_e32 v86, 0x1e3ce508, v86
	v_max_f32_e32 v87, 0x1e3ce508, v87
	v_max_f32_e32 v88, 0x1e3ce508, v88
	v_mul_f32_e32 v78, v78, v82
	v_mul_f32_e32 v79, v79, v83
	v_mul_f32_e32 v80, v80, v84
	v_mul_f32_e32 v81, v81, v85
	v_mul_f32_e32 v77, v77, v89
	v_mul_f32_e32 v82, v74, v86
	v_mul_f32_e32 v83, v75, v87
	v_mul_f32_e32 v84, v76, v88
	v_cvt_pk_bf16_f32 v74, v78, v79
	v_cvt_pk_bf16_f32 v75, v80, v81
	v_cvt_pk_bf16_f32 v76, v82, v83
	v_cvt_pk_bf16_f32 v77, v84, v77
	s_nop 0
	v_lshlrev_b64 v[86:87], 11, v[98:99]
	v_lshl_add_u64 v[86:87], s[26:27], 0, v[86:87]
	v_lshl_add_u64 v[86:87], v[86:87], 0, v[130:131]
	global_store_dwordx4 v[86:87], v[74:77], off
	v_add_u32_e32 v82, 0x80, v176
	v_mad_i64_i32 v[84:85], s[24:25], v82, s44, v[134:135]
	v_lshl_add_u64 v[84:85], v[84:85], 0, s[14:15]
	v_lshl_add_u64 v[88:89], v[84:85], 0, v[130:131]
	v_ashrrev_i32_e32 v83, 31, v82
	s_waitcnt vmcnt(15)
	v_lshlrev_b32_e32 v74, 16, v200
	v_and_b32_e32 v75, 0xffff0000, v200
	v_lshlrev_b32_e32 v76, 16, v201
	v_and_b32_e32 v77, 0xffff0000, v201
	v_lshlrev_b32_e32 v78, 16, v202
	v_and_b32_e32 v79, 0xffff0000, v202
	v_lshlrev_b32_e32 v80, 16, v203
	v_and_b32_e32 v81, 0xffff0000, v203
	v_max_f32_e32 v81, v81, v81
	v_max_f32_e32 v74, v74, v74
	v_max_f32_e32 v75, v75, v75
	v_max_f32_e32 v76, v76, v76
	v_max_f32_e32 v77, v77, v77
	v_max_f32_e32 v78, v78, v78
	v_max_f32_e32 v79, v79, v79
	v_max_f32_e32 v80, v80, v80
	v_max_f32_e32 v81, 0x1e3ce508, v81
	v_max_f32_e32 v74, 0x1e3ce508, v74
	v_max_f32_e32 v75, 0x1e3ce508, v75
	v_max_f32_e32 v76, 0x1e3ce508, v76
	v_max_f32_e32 v77, 0x1e3ce508, v77
	v_max_f32_e32 v78, 0x1e3ce508, v78
	v_max_f32_e32 v79, 0x1e3ce508, v79
	v_max_f32_e32 v80, 0x1e3ce508, v80
	v_mul_f32_e32 v69, v69, v81
	v_mul_f32_e32 v70, v70, v74
	v_mul_f32_e32 v71, v71, v75
	v_mul_f32_e32 v72, v72, v76
	v_mul_f32_e32 v73, v73, v77
	v_mul_f32_e32 v74, v66, v78
	v_mul_f32_e32 v75, v67, v79
	v_mul_f32_e32 v76, v68, v80
	v_cvt_pk_bf16_f32 v66, v70, v71
	v_cvt_pk_bf16_f32 v67, v72, v73
	v_cvt_pk_bf16_f32 v68, v74, v75
	v_cvt_pk_bf16_f32 v69, v76, v69
	global_store_dwordx4 v[86:87], v[66:69], off offset:256
	s_nop 0
	v_lshl_add_u64 v[70:71], v[84:85], 0, v[132:133]
	s_waitcnt vmcnt(15)
	v_lshlrev_b32_e32 v72, 16, v204
	v_and_b32_e32 v66, 0xffff0000, v204
	v_lshlrev_b32_e32 v73, 16, v205
	v_and_b32_e32 v67, 0xffff0000, v205
	v_lshlrev_b32_e32 v75, 16, v207
	v_and_b32_e32 v69, 0xffff0000, v207
	v_lshlrev_b32_e32 v74, 16, v206
	v_and_b32_e32 v68, 0xffff0000, v206
	v_max_f32_e32 v72, v72, v72
	v_max_f32_e32 v66, v66, v66
	v_max_f32_e32 v73, v73, v73
	v_max_f32_e32 v67, v67, v67
	v_max_f32_e32 v69, v69, v69
	v_max_f32_e32 v74, v74, v74
	v_max_f32_e32 v68, v68, v68
	v_max_f32_e32 v75, v75, v75
	v_max_f32_e32 v72, 0x1e3ce508, v72
	v_max_f32_e32 v66, 0x1e3ce508, v66
	v_max_f32_e32 v73, 0x1e3ce508, v73
	v_max_f32_e32 v67, 0x1e3ce508, v67
	v_max_f32_e32 v69, 0x1e3ce508, v69
	v_max_f32_e32 v74, 0x1e3ce508, v74
	v_max_f32_e32 v68, 0x1e3ce508, v68
	v_max_f32_e32 v75, 0x1e3ce508, v75
	v_mul_f32_e32 v62, v62, v72
	v_mul_f32_e32 v63, v63, v66
	v_mul_f32_e32 v64, v64, v73
	v_mul_f32_e32 v65, v65, v67
	v_mul_f32_e32 v61, v61, v69
	v_mul_f32_e32 v66, v58, v74
	v_mul_f32_e32 v67, v59, v68
	v_mul_f32_e32 v68, v60, v75
	v_cvt_pk_bf16_f32 v58, v62, v63
	v_cvt_pk_bf16_f32 v59, v64, v65
	v_cvt_pk_bf16_f32 v60, v66, v67
	v_cvt_pk_bf16_f32 v61, v68, v61
	s_nop 0
	v_lshlrev_b64 v[70:71], 11, v[82:83]
	v_lshl_add_u64 v[70:71], s[26:27], 0, v[70:71]
	v_lshl_add_u64 v[70:71], v[70:71], 0, v[130:131]
	v_add_u32_e32 v66, 0x90, v176
	global_store_dwordx4 v[70:71], v[58:61], off
	v_mad_i64_i32 v[68:69], s[24:25], v66, s44, v[134:135]
	v_lshl_add_u64 v[68:69], v[68:69], 0, s[14:15]
	v_lshl_add_u64 v[72:73], v[68:69], 0, v[130:131]
	v_ashrrev_i32_e32 v67, 31, v66
	s_waitcnt vmcnt(15)
	v_lshlrev_b32_e32 v58, 16, v208
	v_and_b32_e32 v59, 0xffff0000, v208
	v_lshlrev_b32_e32 v60, 16, v209
	v_and_b32_e32 v61, 0xffff0000, v209
	v_lshlrev_b32_e32 v62, 16, v210
	v_and_b32_e32 v63, 0xffff0000, v210
	v_lshlrev_b32_e32 v64, 16, v211
	v_and_b32_e32 v65, 0xffff0000, v211
	v_max_f32_e32 v58, v58, v58
	v_max_f32_e32 v59, v59, v59
	v_max_f32_e32 v60, v60, v60
	v_max_f32_e32 v61, v61, v61
	v_max_f32_e32 v65, v65, v65
	v_max_f32_e32 v62, v62, v62
	v_max_f32_e32 v63, v63, v63
	v_max_f32_e32 v64, v64, v64
	v_max_f32_e32 v58, 0x1e3ce508, v58
	v_max_f32_e32 v59, 0x1e3ce508, v59
	v_max_f32_e32 v60, 0x1e3ce508, v60
	v_max_f32_e32 v61, 0x1e3ce508, v61
	v_max_f32_e32 v65, 0x1e3ce508, v65
	v_max_f32_e32 v62, 0x1e3ce508, v62
	v_max_f32_e32 v63, 0x1e3ce508, v63
	v_max_f32_e32 v64, 0x1e3ce508, v64
	v_mul_f32_e32 v54, v54, v58
	v_mul_f32_e32 v55, v55, v59
	v_mul_f32_e32 v56, v56, v60
	v_mul_f32_e32 v57, v57, v61
	v_mul_f32_e32 v53, v53, v65
	v_mul_f32_e32 v58, v50, v62
	v_mul_f32_e32 v59, v51, v63
	v_mul_f32_e32 v60, v52, v64
	v_cvt_pk_bf16_f32 v50, v54, v55
	v_cvt_pk_bf16_f32 v51, v56, v57
	v_cvt_pk_bf16_f32 v52, v58, v59
	v_cvt_pk_bf16_f32 v53, v60, v53
	s_nop 0
	v_lshl_add_u64 v[58:59], v[68:69], 0, v[132:133]
	global_store_dwordx4 v[70:71], v[50:53], off offset:256
	s_waitcnt vmcnt(15)
; __device__ __forceinline__ unsigned cvt_pk_bf16(float lo, float hi) { unsigned r; asm volatile("v_cvt_pk_bf16_f32 %0, %1, %2" : "=v"(r) : "v"(lo), "v"(hi)); return r; }
; __device__ __forceinline__ float bflo(unsigned u) { return __uint_as_float(u << 16); }
; __device__ __forceinline__ float bfhi(unsigned u) { return __uint_as_float(u & 0xffff0000u); }
; __device__ __forceinline__ float bflo(unsigned u) { return __uint_as_float(u << 16); }
; __device__ __forceinline__ float bfhi(unsigned u) { return __uint_as_float(u & 0xffff0000u); }
;     __device__ __forceinline__ void operator()(const f32x4 (&acc)[2][2][4][2], const Unit& u, int wr, int wc, int fr, int fq) const {
;         const int row0 = u.pm * BM + wr * 64 + fr; const int colt = u.pn * BM + wc * 32 + 8 * fq;
; #pragma unroll
;         for (int ai = 0; ai < 2; ++ai)
; #pragma unroll
;             for (int m = 0; m < 4; ++m) { const size_t row = (size_t)(row0 + ai * HALF + m * 16);
; #pragma unroll
;                 for (int bj = 0; bj < 2; ++bj) { const int col = colt + bj * HALF; const u32x4 gt = *(const u32x4*)(Zg + row * ZW + ZMB + col);
;                     const f32x4 a0 = acc[ai][bj][m][0], a1 = acc[ai][bj][m][1];
;                     u32x4 w; w.x = cvt_pk_bf16(a0[0] * gclamp(bflo(gt.x)), a0[1] * gclamp(bfhi(gt.x))); w.y = cvt_pk_bf16(a0[2] * gclamp(bflo(gt.y)), a0[3] * gclamp(bfhi(gt.y)));
;                     w.z = cvt_pk_bf16(a1[0] * gclamp(bflo(gt.z)), a1[1] * gclamp(bfhi(gt.z))); w.w = cvt_pk_bf16(a1[2] * gclamp(bflo(gt.w)), a1[3] * gclamp(bfhi(gt.w)));
;                     *(u32x4*)(Y + row * DM + col) = w; }
;                 if (m & 1) asm volatile("" ::: "memory"); }
;     }
	s_nop 0
	v_lshlrev_b32_e32 v50, 16, v212
	v_and_b32_e32 v51, 0xffff0000, v212
	v_lshlrev_b32_e32 v52, 16, v213
	v_and_b32_e32 v53, 0xffff0000, v213
	v_lshlrev_b32_e32 v54, 16, v214
	v_and_b32_e32 v55, 0xffff0000, v214
	v_lshlrev_b32_e32 v56, 16, v215
	v_and_b32_e32 v57, 0xffff0000, v215
	v_max_f32_e32 v50, v50, v50
	v_max_f32_e32 v51, v51, v51
	v_max_f32_e32 v52, v52, v52
	v_max_f32_e32 v53, v53, v53
	v_max_f32_e32 v57, v57, v57
	v_max_f32_e32 v54, v54, v54
	v_max_f32_e32 v55, v55, v55
	v_max_f32_e32 v56, v56, v56
	v_max_f32_e32 v50, 0x1e3ce508, v50
	v_max_f32_e32 v51, 0x1e3ce508, v51
	v_max_f32_e32 v52, 0x1e3ce508, v52
	v_max_f32_e32 v53, 0x1e3ce508, v53
	v_max_f32_e32 v57, 0x1e3ce508, v57
	v_max_f32_e32 v54, 0x1e3ce508, v54
	v_max_f32_e32 v55, 0x1e3ce508, v55
	v_max_f32_e32 v56, 0x1e3ce508, v56
	v_mul_f32_e32 v46, v46, v50
	v_mul_f32_e32 v47, v47, v51
	v_mul_f32_e32 v48, v48, v52
	v_mul_f32_e32 v49, v49, v53
	v_mul_f32_e32 v45, v45, v57
	v_mul_f32_e32 v50, v42, v54
	v_mul_f32_e32 v51, v43, v55
	v_mul_f32_e32 v52, v44, v56
	v_cvt_pk_bf16_f32 v42, v46, v47
	v_cvt_pk_bf16_f32 v43, v48, v49
	v_cvt_pk_bf16_f32 v44, v50, v51
	v_cvt_pk_bf16_f32 v45, v52, v45
	s_nop 0
	v_lshlrev_b64 v[54:55], 11, v[66:67]
	v_lshl_add_u64 v[54:55], s[26:27], 0, v[54:55]
	v_lshl_add_u64 v[54:55], v[54:55], 0, v[130:131]
	global_store_dwordx4 v[54:55], v[42:45], off
	v_add_u32_e32 v50, 0xa0, v176
	v_mad_i64_i32 v[52:53], s[24:25], v50, s44, v[134:135]
	v_lshl_add_u64 v[52:53], v[52:53], 0, s[14:15]
	v_lshl_add_u64 v[56:57], v[52:53], 0, v[130:131]
	v_ashrrev_i32_e32 v51, 31, v50
	s_waitcnt vmcnt(15)
	v_lshlrev_b32_e32 v42, 16, v220
	v_and_b32_e32 v43, 0xffff0000, v220
	v_lshlrev_b32_e32 v44, 16, v221
	v_and_b32_e32 v45, 0xffff0000, v221
	v_lshlrev_b32_e32 v46, 16, v222
	v_and_b32_e32 v47, 0xffff0000, v222
	v_lshlrev_b32_e32 v48, 16, v223
	v_and_b32_e32 v49, 0xffff0000, v223
	v_max_f32_e32 v49, v49, v49
	v_max_f32_e32 v42, v42, v42
	v_max_f32_e32 v43, v43, v43
	v_max_f32_e32 v44, v44, v44
	v_max_f32_e32 v45, v45, v45
	v_max_f32_e32 v46, v46, v46
	v_max_f32_e32 v47, v47, v47
	v_max_f32_e32 v48, v48, v48
	v_max_f32_e32 v49, 0x1e3ce508, v49
	v_max_f32_e32 v42, 0x1e3ce508, v42
	v_max_f32_e32 v43, 0x1e3ce508, v43
	v_max_f32_e32 v44, 0x1e3ce508, v44
	v_max_f32_e32 v45, 0x1e3ce508, v45
	v_max_f32_e32 v46, 0x1e3ce508, v46
	v_max_f32_e32 v47, 0x1e3ce508, v47
	v_max_f32_e32 v48, 0x1e3ce508, v48
	v_mul_f32_e32 v37, v37, v49
	v_mul_f32_e32 v38, v38, v42
	v_mul_f32_e32 v39, v39, v43
	v_mul_f32_e32 v40, v40, v44
	v_mul_f32_e32 v41, v41, v45
	v_mul_f32_e32 v42, v34, v46
	v_mul_f32_e32 v43, v35, v47
	v_mul_f32_e32 v44, v36, v48
	v_cvt_pk_bf16_f32 v34, v38, v39
	v_cvt_pk_bf16_f32 v35, v40, v41
	v_cvt_pk_bf16_f32 v36, v42, v43
	v_cvt_pk_bf16_f32 v37, v44, v37
	global_store_dwordx4 v[54:55], v[34:37], off offset:256
	s_nop 0
	v_lshl_add_u64 v[38:39], v[52:53], 0, v[132:133]
	s_waitcnt vmcnt(15)
	v_lshlrev_b32_e32 v40, 16, v224
	v_and_b32_e32 v34, 0xffff0000, v224
	v_lshlrev_b32_e32 v41, 16, v225
	v_and_b32_e32 v35, 0xffff0000, v225
	v_lshlrev_b32_e32 v43, 16, v227
	v_and_b32_e32 v37, 0xffff0000, v227
	v_lshlrev_b32_e32 v42, 16, v226
	v_and_b32_e32 v36, 0xffff0000, v226
	v_max_f32_e32 v40, v40, v40
	v_max_f32_e32 v34, v34, v34
	v_max_f32_e32 v41, v41, v41
	v_max_f32_e32 v35, v35, v35
	v_max_f32_e32 v37, v37, v37
	v_max_f32_e32 v42, v42, v42
	v_max_f32_e32 v36, v36, v36
	v_max_f32_e32 v43, v43, v43
	v_max_f32_e32 v40, 0x1e3ce508, v40
	v_max_f32_e32 v34, 0x1e3ce508, v34
	v_max_f32_e32 v41, 0x1e3ce508, v41
	v_max_f32_e32 v35, 0x1e3ce508, v35
	v_max_f32_e32 v37, 0x1e3ce508, v37
	v_max_f32_e32 v42, 0x1e3ce508, v42
	v_max_f32_e32 v36, 0x1e3ce508, v36
	v_max_f32_e32 v43, 0x1e3ce508, v43
	v_mul_f32_e32 v30, v30, v40
	v_mul_f32_e32 v31, v31, v34
	v_mul_f32_e32 v32, v32, v41
	v_mul_f32_e32 v33, v33, v35
	v_mul_f32_e32 v29, v29, v37
	v_mul_f32_e32 v34, v26, v42
	v_mul_f32_e32 v35, v27, v36
	v_mul_f32_e32 v36, v28, v43
	v_cvt_pk_bf16_f32 v26, v30, v31
	v_cvt_pk_bf16_f32 v27, v32, v33
	v_cvt_pk_bf16_f32 v28, v34, v35
	v_cvt_pk_bf16_f32 v29, v36, v29
	s_nop 0
	v_lshlrev_b64 v[38:39], 11, v[50:51]
	v_lshl_add_u64 v[38:39], s[26:27], 0, v[38:39]
	v_lshl_add_u64 v[38:39], v[38:39], 0, v[130:131]
	v_add_u32_e32 v34, 0xb0, v176
	global_store_dwordx4 v[38:39], v[26:29], off
	v_mad_i64_i32 v[36:37], s[24:25], v34, s44, v[134:135]
	v_lshl_add_u64 v[36:37], v[36:37], 0, s[14:15]
	v_lshl_add_u64 v[40:41], v[36:37], 0, v[130:131]
	v_ashrrev_i32_e32 v35, 31, v34
	s_waitcnt vmcnt(15)
; __device__ __forceinline__ unsigned cvt_pk_bf16(float lo, float hi) { unsigned r; asm volatile("v_cvt_pk_bf16_f32 %0, %1, %2" : "=v"(r) : "v"(lo), "v"(hi)); return r; }
; __device__ __forceinline__ float bflo(unsigned u) { return __uint_as_float(u << 16); }
; __device__ __forceinline__ float bfhi(unsigned u) { return __uint_as_float(u & 0xffff0000u); }
; __device__ __forceinline__ float bflo(unsigned u) { return __uint_as_float(u << 16); }
; __device__ __forceinline__ float bfhi(unsigned u) { return __uint_as_float(u & 0xffff0000u); }
;     __device__ __forceinline__ void operator()(const f32x4 (&acc)[2][2][4][2], const Unit& u, int wr, int wc, int fr, int fq) const {
;         const int row0 = u.pm * BM + wr * 64 + fr; const int colt = u.pn * BM + wc * 32 + 8 * fq;
; #pragma unroll
;         for (int ai = 0; ai < 2; ++ai)
; #pragma unroll
;             for (int m = 0; m < 4; ++m) { const size_t row = (size_t)(row0 + ai * HALF + m * 16);
; #pragma unroll
;                 for (int bj = 0; bj < 2; ++bj) { const int col = colt + bj * HALF; const u32x4 gt = *(const u32x4*)(Zg + row * ZW + ZMB + col);
;                     const f32x4 a0 = acc[ai][bj][m][0], a1 = acc[ai][bj][m][1];
;                     u32x4 w; w.x = cvt_pk_bf16(a0[0] * gclamp(bflo(gt.x)), a0[1] * gclamp(bfhi(gt.x))); w.y = cvt_pk_bf16(a0[2] * gclamp(bflo(gt.y)), a0[3] * gclamp(bfhi(gt.y)));
;                     w.z = cvt_pk_bf16(a1[0] * gclamp(bflo(gt.z)), a1[1] * gclamp(bfhi(gt.z))); w.w = cvt_pk_bf16(a1[2] * gclamp(bflo(gt.w)), a1[3] * gclamp(bfhi(gt.w)));
;                     *(u32x4*)(Y + row * DM + col) = w; }
;                 if (m & 1) asm volatile("" ::: "memory"); }
;     }
	v_lshlrev_b32_e32 v26, 16, v228
	v_and_b32_e32 v27, 0xffff0000, v228
	v_lshlrev_b32_e32 v28, 16, v229
	v_and_b32_e32 v29, 0xffff0000, v229
	v_lshlrev_b32_e32 v30, 16, v230
	v_and_b32_e32 v31, 0xffff0000, v230
	v_lshlrev_b32_e32 v32, 16, v231
	v_and_b32_e32 v33, 0xffff0000, v231
	v_max_f32_e32 v26, v26, v26
	v_max_f32_e32 v27, v27, v27
	v_max_f32_e32 v28, v28, v28
	v_max_f32_e32 v29, v29, v29
	v_max_f32_e32 v33, v33, v33
	v_max_f32_e32 v30, v30, v30
	v_max_f32_e32 v31, v31, v31
	v_max_f32_e32 v32, v32, v32
	v_max_f32_e32 v26, 0x1e3ce508, v26
	v_max_f32_e32 v27, 0x1e3ce508, v27
	v_max_f32_e32 v28, 0x1e3ce508, v28
	v_max_f32_e32 v29, 0x1e3ce508, v29
	v_max_f32_e32 v33, 0x1e3ce508, v33
	v_max_f32_e32 v30, 0x1e3ce508, v30
	v_max_f32_e32 v31, 0x1e3ce508, v31
	v_max_f32_e32 v32, 0x1e3ce508, v32
	v_mul_f32_e32 v22, v22, v26
	v_mul_f32_e32 v23, v23, v27
	v_mul_f32_e32 v24, v24, v28
	v_mul_f32_e32 v25, v25, v29
	v_mul_f32_e32 v21, v21, v33
	v_mul_f32_e32 v26, v18, v30
	v_mul_f32_e32 v27, v19, v31
	v_mul_f32_e32 v28, v20, v32
	v_cvt_pk_bf16_f32 v18, v22, v23
	v_cvt_pk_bf16_f32 v19, v24, v25
	v_cvt_pk_bf16_f32 v20, v26, v27
	v_cvt_pk_bf16_f32 v21, v28, v21
	s_nop 0
	v_lshl_add_u64 v[26:27], v[36:37], 0, v[132:133]
	global_store_dwordx4 v[38:39], v[18:21], off offset:256
	s_waitcnt vmcnt(15)
	s_nop 0
	v_lshlrev_b32_e32 v18, 16, v232
	v_and_b32_e32 v19, 0xffff0000, v232
	v_lshlrev_b32_e32 v20, 16, v233
	v_and_b32_e32 v21, 0xffff0000, v233
	v_lshlrev_b32_e32 v22, 16, v234
	v_and_b32_e32 v23, 0xffff0000, v234
	v_lshlrev_b32_e32 v24, 16, v235
	v_and_b32_e32 v25, 0xffff0000, v235
	v_max_f32_e32 v18, v18, v18
	v_max_f32_e32 v19, v19, v19
	v_max_f32_e32 v20, v20, v20
	v_max_f32_e32 v21, v21, v21
	v_max_f32_e32 v25, v25, v25
	v_max_f32_e32 v22, v22, v22
	v_max_f32_e32 v23, v23, v23
	v_max_f32_e32 v24, v24, v24
	v_max_f32_e32 v18, 0x1e3ce508, v18
	v_max_f32_e32 v19, 0x1e3ce508, v19
	v_max_f32_e32 v20, 0x1e3ce508, v20
	v_max_f32_e32 v21, 0x1e3ce508, v21
	v_max_f32_e32 v25, 0x1e3ce508, v25
	v_max_f32_e32 v22, 0x1e3ce508, v22
	v_max_f32_e32 v23, 0x1e3ce508, v23
	v_max_f32_e32 v24, 0x1e3ce508, v24
	v_mul_f32_e32 v14, v14, v18
	v_mul_f32_e32 v15, v15, v19
	v_mul_f32_e32 v16, v16, v20
	v_mul_f32_e32 v17, v17, v21
	v_mul_f32_e32 v13, v13, v25
	v_mul_f32_e32 v18, v10, v22
	v_mul_f32_e32 v19, v11, v23
	v_mul_f32_e32 v20, v12, v24
	v_cvt_pk_bf16_f32 v10, v14, v15
	v_cvt_pk_bf16_f32 v11, v16, v17
	v_cvt_pk_bf16_f32 v12, v18, v19
	v_cvt_pk_bf16_f32 v13, v20, v13
	s_nop 0
	v_lshlrev_b64 v[18:19], 11, v[34:35]
	v_lshl_add_u64 v[18:19], s[26:27], 0, v[18:19]
	v_lshl_add_u64 v[18:19], v[18:19], 0, v[130:131]
	global_store_dwordx4 v[18:19], v[10:13], off
	s_waitcnt vmcnt(15)
	s_nop 0
	v_lshlrev_b32_e32 v10, 16, v236
	v_and_b32_e32 v11, 0xffff0000, v236
	v_lshlrev_b32_e32 v12, 16, v237
	v_and_b32_e32 v13, 0xffff0000, v237
	v_lshlrev_b32_e32 v14, 16, v238
	v_and_b32_e32 v15, 0xffff0000, v238
	v_lshlrev_b32_e32 v16, 16, v239
	v_and_b32_e32 v17, 0xffff0000, v239
	v_max_f32_e32 v17, v17, v17
	v_max_f32_e32 v10, v10, v10
	v_max_f32_e32 v11, v11, v11
	v_max_f32_e32 v12, v12, v12
	v_max_f32_e32 v13, v13, v13
	v_max_f32_e32 v14, v14, v14
	v_max_f32_e32 v15, v15, v15
	v_max_f32_e32 v16, v16, v16
	v_max_f32_e32 v17, 0x1e3ce508, v17
	v_max_f32_e32 v10, 0x1e3ce508, v10
	v_max_f32_e32 v11, 0x1e3ce508, v11
	v_max_f32_e32 v12, 0x1e3ce508, v12
	v_max_f32_e32 v13, 0x1e3ce508, v13
	v_max_f32_e32 v14, 0x1e3ce508, v14
	v_max_f32_e32 v15, 0x1e3ce508, v15
	v_max_f32_e32 v16, 0x1e3ce508, v16
	v_mul_f32_e32 v5, v5, v17
	v_mul_f32_e32 v6, v6, v10
	v_mul_f32_e32 v7, v7, v11
	v_mul_f32_e32 v8, v8, v12
	v_mul_f32_e32 v9, v9, v13
	v_mul_f32_e32 v10, v2, v14
	v_mul_f32_e32 v11, v3, v15
	v_mul_f32_e32 v12, v4, v16
	v_cvt_pk_bf16_f32 v2, v6, v7
	v_cvt_pk_bf16_f32 v3, v8, v9
	v_cvt_pk_bf16_f32 v4, v10, v11
	v_cvt_pk_bf16_f32 v5, v12, v5
	global_store_dwordx4 v[18:19], v[2:5], off offset:256
	s_cbranch_vccnz .LBB0_694
	s_andn2_b64 vcc, exec, s[6:7]
	s_cbranch_vccnz .LBB0_693
	s_barrier
	s_branch .LBB0_693
